# FFN-in epilogue: all eight row scales of a unit fetched from the LDS table in one batch
# baseline (speedup 1.0000x reference)
.LBB0_491:
	v_lshl_add_u32 v136, s84, 8, v138
	s_lshl_b32 s20, s85, 10
	s_mov_b64 s[68:69], -1
	s_and_b64 vcc, exec, s[52:53]
	v_add_u32_e32 v143, s20, v140
	ds_read_b32 v152, v143 offset:64
	ds_read_b32 v153, v143 offset:128
	ds_read_b32 v154, v143 offset:192
	ds_read_b32 v155, v143 offset:512
	ds_read_b32 v156, v143 offset:576
	ds_read_b32 v157, v143 offset:640
	ds_read_b32 v158, v143 offset:704
	v_ashrrev_i32_e32 v137, 31, v136
	s_mov_b64 s[86:87], 0x30080
	s_cbranch_vccnz .LBB0_493
	ds_read_b32 v144, v143
	s_mov_b64 s[68:69], 0

.LBB0_495:
	s_waitcnt lgkmcnt(0)
	v_mul_f32_e32 v146, 0xbfb8aa3b, v144
	v_pk_mul_f32 v[148:149], v[126:127], v[146:147] op_sel_hi:[1,0]
	v_mul_f32_e32 v144, v144, v144
	v_exp_f32_e32 v148, v148
	v_exp_f32_e32 v149, v149
	v_pk_mul_f32 v[122:123], v[126:127], v[122:123]
	v_pk_mul_f32 v[124:125], v[128:129], v[124:125]
	v_pk_mul_f32 v[120:121], v[116:117], v[120:121]
	v_pk_add_f32 v[148:149], v[148:149], 1.0 op_sel_hi:[1,0]
	v_lshl_or_b32 v134, s90, 7, v141
	v_rcp_f32_e32 v148, v148
	v_rcp_f32_e32 v149, v149
	v_ashrrev_i32_e32 v135, 31, v134
	s_mov_b64 s[68:69], -1
	s_and_b64 vcc, exec, s[52:53]
	v_pk_mul_f32 v[126:127], v[144:145], v[148:149] op_sel_hi:[0,1]
	v_pk_mul_f32 v[122:123], v[122:123], v[126:127]
	v_pk_mul_f32 v[126:127], v[128:129], v[146:147] op_sel_hi:[1,0]
	s_nop 0
	v_exp_f32_e32 v126, v126
	v_exp_f32_e32 v127, v127
	s_nop 0
	v_pk_add_f32 v[126:127], v[126:127], 1.0 op_sel_hi:[1,0]
	s_nop 0
	v_rcp_f32_e32 v126, v126
	v_rcp_f32_e32 v127, v127
	s_nop 0
	v_pk_mul_f32 v[126:127], v[144:145], v[126:127] op_sel_hi:[0,1]
	v_pk_mul_f32 v[124:125], v[124:125], v[126:127]
	v_pk_mul_f32 v[126:127], v[114:115], v[146:147] op_sel_hi:[1,0]
	v_pk_mul_f32 v[114:115], v[114:115], v[118:119]
	v_exp_f32_e32 v126, v126
	v_exp_f32_e32 v127, v127
	s_nop 0
	v_pk_add_f32 v[126:127], v[126:127], 1.0 op_sel_hi:[1,0]
	s_nop 0
	v_rcp_f32_e32 v126, v126
	v_rcp_f32_e32 v127, v127
	s_nop 0
	v_pk_mul_f32 v[118:119], v[144:145], v[126:127] op_sel_hi:[0,1]
	v_pk_mul_f32 v[118:119], v[114:115], v[118:119]
	v_pk_mul_f32 v[114:115], v[116:117], v[146:147] op_sel_hi:[1,0]
	s_nop 0
	v_exp_f32_e32 v114, v114
	v_exp_f32_e32 v115, v115
	s_nop 0
	v_pk_add_f32 v[114:115], v[114:115], 1.0 op_sel_hi:[1,0]
	s_nop 0
	v_rcp_f32_e32 v114, v114
	v_rcp_f32_e32 v115, v115
	s_nop 0
	v_pk_mul_f32 v[114:115], v[144:145], v[114:115] op_sel_hi:[0,1]
	v_pk_mul_f32 v[120:121], v[120:121], v[114:115]
	v_cvt_pk_bf16_f32 v114, v122, v123
	v_cvt_pk_bf16_f32 v115, v124, v125
	v_cvt_pk_bf16_f32 v116, v118, v119
	v_mov_b64_e32 v[118:119], s[40:41]
	v_mad_u64_u32 v[118:119], s[20:21], v136, s17, v[118:119]
	v_cvt_pk_bf16_f32 v117, v120, v121
	v_mov_b32_e32 v120, v119
	v_mad_u64_u32 v[120:121], s[20:21], v137, s17, v[120:121]
	v_mov_b32_e32 v119, v120
	v_lshl_add_u64 v[150:151], v[134:135], 1, v[118:119]
	global_store_dwordx4 v[150:151], v[114:117], off sc1
	s_nop 1
	s_cbranch_vccnz .LBB0_497
	v_mov_b32_e32 v116, v152
	s_mov_b64 s[68:69], 0

.LBB0_499:
	s_waitcnt lgkmcnt(0)
	v_mul_f32_e32 v118, 0xbfb8aa3b, v116
	v_pk_mul_f32 v[120:121], v[110:111], v[118:119] op_sel_hi:[1,0]
	v_mul_f32_e32 v116, v116, v116
	v_exp_f32_e32 v120, v120
	v_exp_f32_e32 v121, v121
	v_pk_mul_f32 v[106:107], v[110:111], v[106:107]
	v_pk_mul_f32 v[108:109], v[112:113], v[108:109]
	v_pk_mul_f32 v[104:105], v[100:101], v[104:105]
	v_pk_add_f32 v[120:121], v[120:121], 1.0 op_sel_hi:[1,0]
	s_mov_b64 s[68:69], -1
	v_rcp_f32_e32 v120, v120
	v_rcp_f32_e32 v121, v121
	s_and_b64 vcc, exec, s[52:53]
	v_pk_mul_f32 v[110:111], v[116:117], v[120:121] op_sel_hi:[0,1]
	v_pk_mul_f32 v[106:107], v[106:107], v[110:111]
	v_pk_mul_f32 v[110:111], v[112:113], v[118:119] op_sel_hi:[1,0]
	s_nop 0
	v_exp_f32_e32 v110, v110
	v_exp_f32_e32 v111, v111
	s_nop 0
	v_pk_add_f32 v[110:111], v[110:111], 1.0 op_sel_hi:[1,0]
	s_nop 0
	v_rcp_f32_e32 v110, v110
	v_rcp_f32_e32 v111, v111
	s_nop 0
	v_pk_mul_f32 v[110:111], v[116:117], v[110:111] op_sel_hi:[0,1]
	v_pk_mul_f32 v[108:109], v[108:109], v[110:111]
	v_pk_mul_f32 v[110:111], v[98:99], v[118:119] op_sel_hi:[1,0]
	v_pk_mul_f32 v[98:99], v[98:99], v[102:103]
	v_exp_f32_e32 v110, v110
	v_exp_f32_e32 v111, v111
	s_nop 0
	v_pk_add_f32 v[110:111], v[110:111], 1.0 op_sel_hi:[1,0]
	s_nop 0
	v_rcp_f32_e32 v110, v110
	v_rcp_f32_e32 v111, v111
	s_nop 0
	v_pk_mul_f32 v[102:103], v[116:117], v[110:111] op_sel_hi:[0,1]
	v_pk_mul_f32 v[102:103], v[98:99], v[102:103]
	v_pk_mul_f32 v[98:99], v[100:101], v[118:119] op_sel_hi:[1,0]
	s_nop 0
	v_exp_f32_e32 v98, v98
	v_exp_f32_e32 v99, v99
	s_nop 0
	v_pk_add_f32 v[98:99], v[98:99], 1.0 op_sel_hi:[1,0]
	s_nop 0
	v_rcp_f32_e32 v98, v98
	v_rcp_f32_e32 v99, v99
	s_nop 0
	v_pk_mul_f32 v[98:99], v[116:117], v[98:99] op_sel_hi:[0,1]
	v_pk_mul_f32 v[104:105], v[104:105], v[98:99]
	v_cvt_pk_bf16_f32 v98, v106, v107
	v_cvt_pk_bf16_f32 v99, v108, v109
	v_cvt_pk_bf16_f32 v100, v102, v103
	v_cvt_pk_bf16_f32 v101, v104, v105
	s_mul_i32 s20, s17, 0x10
	s_mov_b32 s21, 0
	v_lshl_add_u64 v[102:103], s[20:21], 0, v[150:151]
	global_store_dwordx4 v[102:103], v[98:101], off sc1
	s_nop 1
	s_cbranch_vccnz .LBB0_501
	v_mov_b32_e32 v100, v153
	s_mov_b64 s[68:69], 0

.LBB0_503:
	s_waitcnt lgkmcnt(0)
	v_mul_f32_e32 v102, 0xbfb8aa3b, v100
	v_pk_mul_f32 v[104:105], v[94:95], v[102:103] op_sel_hi:[1,0]
	v_mul_f32_e32 v100, v100, v100
	v_exp_f32_e32 v104, v104
	v_exp_f32_e32 v105, v105
	v_pk_mul_f32 v[90:91], v[94:95], v[90:91]
	v_pk_mul_f32 v[92:93], v[96:97], v[92:93]
	v_pk_mul_f32 v[88:89], v[84:85], v[88:89]
	v_pk_add_f32 v[104:105], v[104:105], 1.0 op_sel_hi:[1,0]
	s_mov_b64 s[68:69], -1
	v_rcp_f32_e32 v104, v104
	v_rcp_f32_e32 v105, v105
	s_and_b64 vcc, exec, s[52:53]
	v_pk_mul_f32 v[94:95], v[100:101], v[104:105] op_sel_hi:[0,1]
	v_pk_mul_f32 v[90:91], v[90:91], v[94:95]
	v_pk_mul_f32 v[94:95], v[96:97], v[102:103] op_sel_hi:[1,0]
	s_nop 0
	v_exp_f32_e32 v94, v94
	v_exp_f32_e32 v95, v95
	s_nop 0
	v_pk_add_f32 v[94:95], v[94:95], 1.0 op_sel_hi:[1,0]
	s_nop 0
	v_rcp_f32_e32 v94, v94
	v_rcp_f32_e32 v95, v95
	s_nop 0
	v_pk_mul_f32 v[94:95], v[100:101], v[94:95] op_sel_hi:[0,1]
	v_pk_mul_f32 v[92:93], v[92:93], v[94:95]
	v_pk_mul_f32 v[94:95], v[82:83], v[102:103] op_sel_hi:[1,0]
	v_pk_mul_f32 v[82:83], v[82:83], v[86:87]
	v_exp_f32_e32 v94, v94
	v_exp_f32_e32 v95, v95
	s_nop 0
	v_pk_add_f32 v[94:95], v[94:95], 1.0 op_sel_hi:[1,0]
	s_nop 0
	v_rcp_f32_e32 v94, v94
	v_rcp_f32_e32 v95, v95
	s_nop 0
	v_pk_mul_f32 v[86:87], v[100:101], v[94:95] op_sel_hi:[0,1]
	v_pk_mul_f32 v[86:87], v[82:83], v[86:87]
	v_pk_mul_f32 v[82:83], v[84:85], v[102:103] op_sel_hi:[1,0]
	s_nop 0
	v_exp_f32_e32 v82, v82
	v_exp_f32_e32 v83, v83
	s_nop 0
	v_pk_add_f32 v[82:83], v[82:83], 1.0 op_sel_hi:[1,0]
	s_nop 0
	v_rcp_f32_e32 v82, v82
	v_rcp_f32_e32 v83, v83
	s_nop 0
	v_pk_mul_f32 v[82:83], v[100:101], v[82:83] op_sel_hi:[0,1]
	v_pk_mul_f32 v[88:89], v[88:89], v[82:83]
	v_cvt_pk_bf16_f32 v82, v90, v91
	v_cvt_pk_bf16_f32 v83, v92, v93
	v_cvt_pk_bf16_f32 v84, v86, v87
	v_cvt_pk_bf16_f32 v85, v88, v89
	s_mul_i32 s20, s17, 0x20
	s_mov_b32 s21, 0
	v_lshl_add_u64 v[86:87], s[20:21], 0, v[150:151]
	global_store_dwordx4 v[86:87], v[82:85], off sc1
	s_nop 1
	s_cbranch_vccnz .LBB0_505
	v_mov_b32_e32 v84, v154
	s_mov_b64 s[68:69], 0

.LBB0_507:
	s_waitcnt lgkmcnt(0)
	v_mul_f32_e32 v86, 0xbfb8aa3b, v84
	v_pk_mul_f32 v[88:89], v[78:79], v[86:87] op_sel_hi:[1,0]
	v_mul_f32_e32 v84, v84, v84
	v_exp_f32_e32 v88, v88
	v_exp_f32_e32 v89, v89
	v_pk_mul_f32 v[74:75], v[78:79], v[74:75]
	v_pk_mul_f32 v[76:77], v[80:81], v[76:77]
	v_pk_mul_f32 v[72:73], v[68:69], v[72:73]
	v_pk_add_f32 v[88:89], v[88:89], 1.0 op_sel_hi:[1,0]
	s_mov_b64 s[68:69], -1
	v_rcp_f32_e32 v88, v88
	v_rcp_f32_e32 v89, v89
	s_and_b64 vcc, exec, s[52:53]
	v_pk_mul_f32 v[78:79], v[84:85], v[88:89] op_sel_hi:[0,1]
	v_pk_mul_f32 v[74:75], v[74:75], v[78:79]
	v_pk_mul_f32 v[78:79], v[80:81], v[86:87] op_sel_hi:[1,0]
	s_nop 0
	v_exp_f32_e32 v78, v78
	v_exp_f32_e32 v79, v79
	s_nop 0
	v_pk_add_f32 v[78:79], v[78:79], 1.0 op_sel_hi:[1,0]
	s_nop 0
	v_rcp_f32_e32 v78, v78
	v_rcp_f32_e32 v79, v79
	s_nop 0
	v_pk_mul_f32 v[78:79], v[84:85], v[78:79] op_sel_hi:[0,1]
	v_pk_mul_f32 v[76:77], v[76:77], v[78:79]
	v_pk_mul_f32 v[78:79], v[66:67], v[86:87] op_sel_hi:[1,0]
	v_pk_mul_f32 v[66:67], v[66:67], v[70:71]
	v_exp_f32_e32 v78, v78
	v_exp_f32_e32 v79, v79
	s_nop 0
	v_pk_add_f32 v[78:79], v[78:79], 1.0 op_sel_hi:[1,0]
	s_nop 0
	v_rcp_f32_e32 v78, v78
	v_rcp_f32_e32 v79, v79
	s_nop 0
	v_pk_mul_f32 v[70:71], v[84:85], v[78:79] op_sel_hi:[0,1]
	v_pk_mul_f32 v[70:71], v[66:67], v[70:71]
	v_pk_mul_f32 v[66:67], v[68:69], v[86:87] op_sel_hi:[1,0]
	s_nop 0
	v_exp_f32_e32 v66, v66
	v_exp_f32_e32 v67, v67
	s_nop 0
	v_pk_add_f32 v[66:67], v[66:67], 1.0 op_sel_hi:[1,0]
	s_nop 0
	v_rcp_f32_e32 v66, v66
	v_rcp_f32_e32 v67, v67
	s_nop 0
	v_pk_mul_f32 v[66:67], v[84:85], v[66:67] op_sel_hi:[0,1]
	v_pk_mul_f32 v[72:73], v[72:73], v[66:67]
	v_cvt_pk_bf16_f32 v66, v74, v75
	v_cvt_pk_bf16_f32 v67, v76, v77
	v_cvt_pk_bf16_f32 v68, v70, v71
	v_cvt_pk_bf16_f32 v69, v72, v73
	s_mul_i32 s20, s17, 0x30
	s_mov_b32 s21, 0
	v_lshl_add_u64 v[70:71], s[20:21], 0, v[150:151]
	global_store_dwordx4 v[70:71], v[66:69], off sc1
	s_nop 1
	s_cbranch_vccnz .LBB0_509
	v_mov_b32_e32 v68, v155
	s_mov_b64 s[68:69], 0

.LBB0_511:
	s_waitcnt lgkmcnt(0)
	v_mul_f32_e32 v70, 0xbfb8aa3b, v68
	v_pk_mul_f32 v[72:73], v[62:63], v[70:71] op_sel_hi:[1,0]
	v_mul_f32_e32 v68, v68, v68
	v_exp_f32_e32 v72, v72
	v_exp_f32_e32 v73, v73
	v_pk_mul_f32 v[58:59], v[62:63], v[58:59]
	v_pk_mul_f32 v[60:61], v[64:65], v[60:61]
	v_pk_mul_f32 v[56:57], v[52:53], v[56:57]
	v_pk_add_f32 v[72:73], v[72:73], 1.0 op_sel_hi:[1,0]
	s_mov_b64 s[68:69], -1
	v_rcp_f32_e32 v72, v72
	v_rcp_f32_e32 v73, v73
	s_and_b64 vcc, exec, s[52:53]
	v_pk_mul_f32 v[62:63], v[68:69], v[72:73] op_sel_hi:[0,1]
	v_pk_mul_f32 v[58:59], v[58:59], v[62:63]
	v_pk_mul_f32 v[62:63], v[64:65], v[70:71] op_sel_hi:[1,0]
	s_nop 0
	v_exp_f32_e32 v62, v62
	v_exp_f32_e32 v63, v63
	s_nop 0
	v_pk_add_f32 v[62:63], v[62:63], 1.0 op_sel_hi:[1,0]
	s_nop 0
	v_rcp_f32_e32 v62, v62
	v_rcp_f32_e32 v63, v63
	s_nop 0
	v_pk_mul_f32 v[62:63], v[68:69], v[62:63] op_sel_hi:[0,1]
	v_pk_mul_f32 v[60:61], v[60:61], v[62:63]
	v_pk_mul_f32 v[62:63], v[50:51], v[70:71] op_sel_hi:[1,0]
	v_pk_mul_f32 v[50:51], v[50:51], v[54:55]
	v_exp_f32_e32 v62, v62
	v_exp_f32_e32 v63, v63
	s_nop 0
	v_pk_add_f32 v[62:63], v[62:63], 1.0 op_sel_hi:[1,0]
	s_nop 0
	v_rcp_f32_e32 v62, v62
	v_rcp_f32_e32 v63, v63
	s_nop 0
	v_pk_mul_f32 v[54:55], v[68:69], v[62:63] op_sel_hi:[0,1]
	v_pk_mul_f32 v[54:55], v[50:51], v[54:55]
	v_pk_mul_f32 v[50:51], v[52:53], v[70:71] op_sel_hi:[1,0]
	s_nop 0
	v_exp_f32_e32 v50, v50
	v_exp_f32_e32 v51, v51
	s_nop 0
	v_pk_add_f32 v[50:51], v[50:51], 1.0 op_sel_hi:[1,0]
	s_nop 0
	v_rcp_f32_e32 v50, v50
	v_rcp_f32_e32 v51, v51
	s_nop 0
	v_pk_mul_f32 v[50:51], v[68:69], v[50:51] op_sel_hi:[0,1]
	v_pk_mul_f32 v[56:57], v[56:57], v[50:51]
	v_cvt_pk_bf16_f32 v50, v58, v59
	v_cvt_pk_bf16_f32 v51, v60, v61
	v_cvt_pk_bf16_f32 v52, v54, v55
	v_cvt_pk_bf16_f32 v53, v56, v57
	s_mul_i32 s20, s17, 0x80
	s_mov_b32 s21, 0
	v_lshl_add_u64 v[54:55], s[20:21], 0, v[150:151]
	global_store_dwordx4 v[54:55], v[50:53], off sc1
	s_nop 1
	s_cbranch_vccnz .LBB0_513
	v_mov_b32_e32 v52, v156
	s_mov_b64 s[68:69], 0

.LBB0_515:
	s_waitcnt lgkmcnt(0)
	v_mul_f32_e32 v54, 0xbfb8aa3b, v52
	v_pk_mul_f32 v[56:57], v[46:47], v[54:55] op_sel_hi:[1,0]
	v_mul_f32_e32 v52, v52, v52
	v_exp_f32_e32 v56, v56
	v_exp_f32_e32 v57, v57
	v_pk_mul_f32 v[42:43], v[46:47], v[42:43]
	v_pk_mul_f32 v[44:45], v[48:49], v[44:45]
	v_pk_mul_f32 v[40:41], v[36:37], v[40:41]
	v_pk_add_f32 v[56:57], v[56:57], 1.0 op_sel_hi:[1,0]
	s_mov_b64 s[68:69], -1
	v_rcp_f32_e32 v56, v56
	v_rcp_f32_e32 v57, v57
	s_and_b64 vcc, exec, s[52:53]
	v_pk_mul_f32 v[46:47], v[52:53], v[56:57] op_sel_hi:[0,1]
	v_pk_mul_f32 v[42:43], v[42:43], v[46:47]
	v_pk_mul_f32 v[46:47], v[48:49], v[54:55] op_sel_hi:[1,0]
	s_nop 0
	v_exp_f32_e32 v46, v46
	v_exp_f32_e32 v47, v47
	s_nop 0
	v_pk_add_f32 v[46:47], v[46:47], 1.0 op_sel_hi:[1,0]
	s_nop 0
	v_rcp_f32_e32 v46, v46
	v_rcp_f32_e32 v47, v47
	s_nop 0
	v_pk_mul_f32 v[46:47], v[52:53], v[46:47] op_sel_hi:[0,1]
	v_pk_mul_f32 v[44:45], v[44:45], v[46:47]
	v_pk_mul_f32 v[46:47], v[34:35], v[54:55] op_sel_hi:[1,0]
	v_pk_mul_f32 v[34:35], v[34:35], v[38:39]
	v_exp_f32_e32 v46, v46
	v_exp_f32_e32 v47, v47
	s_nop 0
	v_pk_add_f32 v[46:47], v[46:47], 1.0 op_sel_hi:[1,0]
	s_nop 0
	v_rcp_f32_e32 v46, v46
	v_rcp_f32_e32 v47, v47
	s_nop 0
	v_pk_mul_f32 v[38:39], v[52:53], v[46:47] op_sel_hi:[0,1]
	v_pk_mul_f32 v[38:39], v[34:35], v[38:39]
	v_pk_mul_f32 v[34:35], v[36:37], v[54:55] op_sel_hi:[1,0]
	s_nop 0
	v_exp_f32_e32 v34, v34
	v_exp_f32_e32 v35, v35
	s_nop 0
	v_pk_add_f32 v[34:35], v[34:35], 1.0 op_sel_hi:[1,0]
	s_nop 0
	v_rcp_f32_e32 v34, v34
	v_rcp_f32_e32 v35, v35
	s_nop 0
	v_pk_mul_f32 v[34:35], v[52:53], v[34:35] op_sel_hi:[0,1]
	v_pk_mul_f32 v[40:41], v[40:41], v[34:35]
	v_cvt_pk_bf16_f32 v34, v42, v43
	v_cvt_pk_bf16_f32 v35, v44, v45
	v_cvt_pk_bf16_f32 v36, v38, v39
	v_cvt_pk_bf16_f32 v37, v40, v41
	s_mul_i32 s20, s17, 0x90
	s_mov_b32 s21, 0
	v_lshl_add_u64 v[38:39], s[20:21], 0, v[150:151]
	global_store_dwordx4 v[38:39], v[34:37], off sc1
	s_nop 1
	s_cbranch_vccnz .LBB0_517
	v_mov_b32_e32 v36, v157
	s_mov_b64 s[68:69], 0

.LBB0_519:
	s_waitcnt lgkmcnt(0)
	v_mul_f32_e32 v38, 0xbfb8aa3b, v36
	v_pk_mul_f32 v[40:41], v[30:31], v[38:39] op_sel_hi:[1,0]
	v_mul_f32_e32 v36, v36, v36
	v_exp_f32_e32 v40, v40
	v_exp_f32_e32 v41, v41
	v_pk_mul_f32 v[26:27], v[30:31], v[26:27]
	v_pk_mul_f32 v[28:29], v[32:33], v[28:29]
	v_pk_mul_f32 v[24:25], v[20:21], v[24:25]
	v_pk_add_f32 v[40:41], v[40:41], 1.0 op_sel_hi:[1,0]
	s_mov_b64 s[68:69], -1
	v_rcp_f32_e32 v40, v40
	v_rcp_f32_e32 v41, v41
	s_and_b64 vcc, exec, s[52:53]
	v_pk_mul_f32 v[30:31], v[36:37], v[40:41] op_sel_hi:[0,1]
	v_pk_mul_f32 v[26:27], v[26:27], v[30:31]
	v_pk_mul_f32 v[30:31], v[32:33], v[38:39] op_sel_hi:[1,0]
	s_nop 0
	v_exp_f32_e32 v30, v30
	v_exp_f32_e32 v31, v31
	s_nop 0
	v_pk_add_f32 v[30:31], v[30:31], 1.0 op_sel_hi:[1,0]
	s_nop 0
	v_rcp_f32_e32 v30, v30
	v_rcp_f32_e32 v31, v31
	s_nop 0
	v_pk_mul_f32 v[30:31], v[36:37], v[30:31] op_sel_hi:[0,1]
	v_pk_mul_f32 v[28:29], v[28:29], v[30:31]
	v_pk_mul_f32 v[30:31], v[18:19], v[38:39] op_sel_hi:[1,0]
	v_pk_mul_f32 v[18:19], v[18:19], v[22:23]
	v_exp_f32_e32 v30, v30
	v_exp_f32_e32 v31, v31
	s_nop 0
	v_pk_add_f32 v[30:31], v[30:31], 1.0 op_sel_hi:[1,0]
	s_nop 0
	v_rcp_f32_e32 v30, v30
	v_rcp_f32_e32 v31, v31
	s_nop 0
	v_pk_mul_f32 v[22:23], v[36:37], v[30:31] op_sel_hi:[0,1]
	v_pk_mul_f32 v[22:23], v[18:19], v[22:23]
	v_pk_mul_f32 v[18:19], v[20:21], v[38:39] op_sel_hi:[1,0]
	s_nop 0
	v_exp_f32_e32 v18, v18
	v_exp_f32_e32 v19, v19
	s_nop 0
	v_pk_add_f32 v[18:19], v[18:19], 1.0 op_sel_hi:[1,0]
	s_nop 0
	v_rcp_f32_e32 v18, v18
	v_rcp_f32_e32 v19, v19
	s_nop 0
	v_pk_mul_f32 v[18:19], v[36:37], v[18:19] op_sel_hi:[0,1]
	v_pk_mul_f32 v[24:25], v[24:25], v[18:19]
	v_cvt_pk_bf16_f32 v18, v26, v27
	v_cvt_pk_bf16_f32 v19, v28, v29
	v_cvt_pk_bf16_f32 v20, v22, v23
	v_cvt_pk_bf16_f32 v21, v24, v25
	s_mul_i32 s20, s17, 0xa0
	s_mov_b32 s21, 0
	v_lshl_add_u64 v[22:23], s[20:21], 0, v[150:151]
	global_store_dwordx4 v[22:23], v[18:21], off sc1
	s_nop 1
	s_cbranch_vccnz .LBB0_521
	v_mov_b32_e32 v20, v158
	s_mov_b64 s[68:69], 0
